# weight conversion items: 32 row loads in flight per item, scalar row stepping (was 4 drained trips of 8 with 64-bit VALU address math)
# baseline (speedup 1.0000x reference)
; __device__ __forceinline__ unsigned cvt_pk_bf16(float lo, float hi) { const f32x2 v = {lo, hi}; const bf16x2_t b = __builtin_convertvector(v, bf16x2_t); return __builtin_bit_cast(unsigned, b); }
; __device__ __forceinline__ void transpose_item(const float* __restrict__ W, int K, int N, bf16_t* __restrict__ WT, int pt, float* scr, int item, int lane) {
;     ...
;     for (int i = 0; i < 32; ++i) { const int kk = 2 * i + (lane >> 5); scr[kk * 33 + (lane & 31)] = __builtin_nontemporal_load(&W[(size_t)(k0 + kk) * N + n0 + (lane & 31)]); }
;     asm volatile("s_waitcnt lgkmcnt(0)" ::: "memory");
;     const int c = lane & 7;
; #pragma unroll
;     for (int j = 0; j < 4; ++j) { const int n = (lane >> 3) + 8 * j; const float* s = scr + (8 * c) * 33 + n;
;         u32x4 o; o.x = cvt_pk_bf16(s[0 * 33], s[1 * 33]); o.y = cvt_pk_bf16(s[2 * 33], s[3 * 33]); o.z = cvt_pk_bf16(s[4 * 33], s[5 * 33]); o.w = cvt_pk_bf16(s[6 * 33], s[7 * 33]);
;         *(u32x4*)(WT + (size_t)permrow(pt, n0 + n) * K + k0 + 8 * c) = o; }
.LBB0_491:
	v_mul_lo_u32 v5, v1, s31
	v_lshl_add_u32 v5, v5, 2, v144
	s_lshl_b32 s17, s31, 3
	s_mov_b64 s[40:41], s[20:21]
	global_load_dword v48, v5, s[40:41] nt
	s_add_u32 s40, s40, s17
	s_addc_u32 s41, s41, 0
	global_load_dword v49, v5, s[40:41] nt
	s_add_u32 s40, s40, s17
	s_addc_u32 s41, s41, 0
	global_load_dword v50, v5, s[40:41] nt
	s_add_u32 s40, s40, s17
	s_addc_u32 s41, s41, 0
	global_load_dword v51, v5, s[40:41] nt
	s_add_u32 s40, s40, s17
	s_addc_u32 s41, s41, 0
	global_load_dword v52, v5, s[40:41] nt
	s_add_u32 s40, s40, s17
	s_addc_u32 s41, s41, 0
	global_load_dword v53, v5, s[40:41] nt
	s_add_u32 s40, s40, s17
	s_addc_u32 s41, s41, 0
	global_load_dword v54, v5, s[40:41] nt
	s_add_u32 s40, s40, s17
	s_addc_u32 s41, s41, 0
	global_load_dword v55, v5, s[40:41] nt
	s_add_u32 s40, s40, s17
	s_addc_u32 s41, s41, 0
	global_load_dword v56, v5, s[40:41] nt
	s_add_u32 s40, s40, s17
	s_addc_u32 s41, s41, 0
	global_load_dword v57, v5, s[40:41] nt
	s_add_u32 s40, s40, s17
	s_addc_u32 s41, s41, 0
	global_load_dword v58, v5, s[40:41] nt
	s_add_u32 s40, s40, s17
	s_addc_u32 s41, s41, 0
	global_load_dword v59, v5, s[40:41] nt
	s_add_u32 s40, s40, s17
	s_addc_u32 s41, s41, 0
	global_load_dword v60, v5, s[40:41] nt
	s_add_u32 s40, s40, s17
	s_addc_u32 s41, s41, 0
	global_load_dword v61, v5, s[40:41] nt
	s_add_u32 s40, s40, s17
	s_addc_u32 s41, s41, 0
	global_load_dword v62, v5, s[40:41] nt
	s_add_u32 s40, s40, s17
	s_addc_u32 s41, s41, 0
	global_load_dword v63, v5, s[40:41] nt
	s_add_u32 s40, s40, s17
	s_addc_u32 s41, s41, 0
	global_load_dword v64, v5, s[40:41] nt
	s_add_u32 s40, s40, s17
	s_addc_u32 s41, s41, 0
	global_load_dword v65, v5, s[40:41] nt
	s_add_u32 s40, s40, s17
	s_addc_u32 s41, s41, 0
	global_load_dword v66, v5, s[40:41] nt
	s_add_u32 s40, s40, s17
	s_addc_u32 s41, s41, 0
	global_load_dword v67, v5, s[40:41] nt
	s_add_u32 s40, s40, s17
	s_addc_u32 s41, s41, 0
	global_load_dword v68, v5, s[40:41] nt
	s_add_u32 s40, s40, s17
	s_addc_u32 s41, s41, 0
	global_load_dword v69, v5, s[40:41] nt
	s_add_u32 s40, s40, s17
	s_addc_u32 s41, s41, 0
	global_load_dword v70, v5, s[40:41] nt
	s_add_u32 s40, s40, s17
	s_addc_u32 s41, s41, 0
	global_load_dword v71, v5, s[40:41] nt
	s_add_u32 s40, s40, s17
	s_addc_u32 s41, s41, 0
	global_load_dword v72, v5, s[40:41] nt
	s_add_u32 s40, s40, s17
	s_addc_u32 s41, s41, 0
	global_load_dword v73, v5, s[40:41] nt
	s_add_u32 s40, s40, s17
	s_addc_u32 s41, s41, 0
	global_load_dword v74, v5, s[40:41] nt
	s_add_u32 s40, s40, s17
	s_addc_u32 s41, s41, 0
	global_load_dword v75, v5, s[40:41] nt
	s_add_u32 s40, s40, s17
	s_addc_u32 s41, s41, 0
	global_load_dword v76, v5, s[40:41] nt
	s_add_u32 s40, s40, s17
	s_addc_u32 s41, s41, 0
	global_load_dword v77, v5, s[40:41] nt
	s_add_u32 s40, s40, s17
	s_addc_u32 s41, s41, 0
	global_load_dword v78, v5, s[40:41] nt
	s_add_u32 s40, s40, s17
	s_addc_u32 s41, s41, 0
	global_load_dword v79, v5, s[40:41] nt
	v_mov_b32_e32 v6, v4
	v_add_u32_e32 v7, 0x400, v4
	s_waitcnt vmcnt(30)
	ds_write2_b32 v6, v48, v49 offset1:66
	s_waitcnt vmcnt(28)
	ds_write2_b32 v6, v50, v51 offset0:132 offset1:198
	s_waitcnt vmcnt(26)
	ds_write2_b32 v7, v52, v53 offset0:8 offset1:74
	s_waitcnt vmcnt(24)
	ds_write2_b32 v7, v54, v55 offset0:140 offset1:206
	v_add_u32_e32 v6, 0x840, v4
	v_add_u32_e32 v7, 0xc40, v4
	s_waitcnt vmcnt(22)
	ds_write2_b32 v6, v56, v57 offset1:66
	s_waitcnt vmcnt(20)
	ds_write2_b32 v6, v58, v59 offset0:132 offset1:198
	s_waitcnt vmcnt(18)
	ds_write2_b32 v7, v60, v61 offset0:8 offset1:74
	s_waitcnt vmcnt(16)
	ds_write2_b32 v7, v62, v63 offset0:140 offset1:206
	v_add_u32_e32 v6, 0x1080, v4
	v_add_u32_e32 v7, 0x1480, v4
	s_waitcnt vmcnt(14)
	ds_write2_b32 v6, v64, v65 offset1:66
	s_waitcnt vmcnt(12)
	ds_write2_b32 v6, v66, v67 offset0:132 offset1:198
	s_waitcnt vmcnt(10)
	ds_write2_b32 v7, v68, v69 offset0:8 offset1:74
	s_waitcnt vmcnt(8)
	ds_write2_b32 v7, v70, v71 offset0:140 offset1:206
	v_add_u32_e32 v6, 0x18c0, v4
	v_add_u32_e32 v7, 0x1cc0, v4
	s_waitcnt vmcnt(6)
	ds_write2_b32 v6, v72, v73 offset1:66
	s_waitcnt vmcnt(4)
	ds_write2_b32 v6, v74, v75 offset0:132 offset1:198
	s_waitcnt vmcnt(2)
	ds_write2_b32 v7, v76, v77 offset0:8 offset1:74
	s_waitcnt vmcnt(0)
	ds_write2_b32 v7, v78, v79 offset0:140 offset1:206
	s_waitcnt lgkmcnt(0)
	ds_read2_b32 v[4:5], v14 offset1:33
	ds_read2_b32 v[6:7], v14 offset0:66 offset1:99
	ds_read2_b32 v[8:9], v14 offset0:132 offset1:165
	ds_read2_b32 v[10:11], v14 offset0:198 offset1:231
	s_lshl_b32 s31, s34, 6
	s_lshr_b32 s20, s16, 1
	s_and_b32 s17, s31, 0x80
	s_and_b32 s21, s20, 64
	s_or_b32 s35, s21, s17
	s_and_b32 s34, s20, 0x70
	v_or_b32_e32 v1, s16, v13
	s_cmp_lt_i32 s30, 2
	s_mov_b64 s[20:21], -1
	s_cbranch_scc1 .LBB0_498
	s_cmp_gt_i32 s30, 2
	v_cmp_lt_i32_e32 vcc, s45, v1
	s_cbranch_scc0 .LBB0_495
	v_and_b32_e32 v2, 0xffffff27, v1
	v_or_b32_e32 v2, s35, v2
	v_cndmask_b32_e32 v19, v2, v1, vcc
	s_mov_b64 s[20:21], 0
